# v12 + per-instance relaxed peeled waits (YA 40, YB 56, EpiSsq 32)
# speedup vs baseline: 1.0115x; 1.0115x over previous
.LBB0_80:
	s_add_u32 s2, s14, 0x100
	v_mov_b32_e32 v0, 0
	s_addc_u32 s8, s15, 0
	s_mov_b32 s9, -2
	v_mov_b32_e32 v1, v0
	v_mov_b32_e32 v2, v0
	v_mov_b32_e32 v3, v0
	v_mov_b32_e32 v6, v0
	s_waitcnt lgkmcnt(0)
	v_mov_b32_e32 v7, v0
	v_mov_b32_e32 v8, v0
	v_mov_b32_e32 v9, v0
	v_mov_b32_e32 v18, v0
	v_mov_b32_e32 v19, v0
	v_mov_b32_e32 v20, v0
	v_mov_b32_e32 v21, v0
	v_mov_b32_e32 v22, v0
	v_mov_b32_e32 v23, v0
	v_mov_b32_e32 v24, v0
	v_mov_b32_e32 v25, v0
	v_mov_b32_e32 v34, v0
	v_mov_b32_e32 v35, v0
	v_mov_b32_e32 v36, v0
	v_mov_b32_e32 v37, v0
	v_mov_b32_e32 v38, v0
	v_mov_b32_e32 v39, v0
	v_mov_b32_e32 v40, v0
	v_mov_b32_e32 v41, v0
	v_mov_b32_e32 v50, v0
	v_mov_b32_e32 v51, v0
	v_mov_b32_e32 v52, v0
	v_mov_b32_e32 v53, v0
	v_mov_b32_e32 v54, v0
	v_mov_b32_e32 v55, v0
	v_mov_b32_e32 v56, v0
	v_mov_b32_e32 v57, v0
	v_mov_b32_e32 v10, v0
	v_mov_b32_e32 v11, v0
	v_mov_b32_e32 v12, v0
	v_mov_b32_e32 v13, v0
	v_mov_b32_e32 v14, v0
	v_mov_b32_e32 v15, v0
	v_mov_b32_e32 v16, v0
	v_mov_b32_e32 v17, v0
	v_mov_b32_e32 v26, v0
	v_mov_b32_e32 v27, v0
	v_mov_b32_e32 v28, v0
	v_mov_b32_e32 v29, v0
	v_mov_b32_e32 v30, v0
	v_mov_b32_e32 v31, v0
	v_mov_b32_e32 v32, v0
	v_mov_b32_e32 v33, v0
	v_mov_b32_e32 v42, v0
	v_mov_b32_e32 v43, v0
	v_mov_b32_e32 v44, v0
	v_mov_b32_e32 v45, v0
	v_mov_b32_e32 v46, v0
	v_mov_b32_e32 v47, v0
	v_mov_b32_e32 v48, v0
	v_mov_b32_e32 v49, v0
	v_mov_b32_e32 v58, v0
	v_mov_b32_e32 v59, v0
	v_mov_b32_e32 v60, v0
	v_mov_b32_e32 v61, v0
	v_mov_b32_e32 v62, v0
	v_mov_b32_e32 v63, v0
	v_mov_b32_e32 v64, v0
	v_mov_b32_e32 v65, v0
	v_mov_b32_e32 v66, v0
	v_mov_b32_e32 v67, v0
	v_mov_b32_e32 v68, v0
	v_mov_b32_e32 v69, v0
	v_mov_b32_e32 v70, v0
	v_mov_b32_e32 v71, v0
	v_mov_b32_e32 v72, v0
	v_mov_b32_e32 v73, v0
	v_mov_b32_e32 v82, v0
	v_mov_b32_e32 v83, v0
	v_mov_b32_e32 v84, v0
	v_mov_b32_e32 v85, v0
	v_mov_b32_e32 v86, v0
	v_mov_b32_e32 v87, v0
	v_mov_b32_e32 v88, v0
	v_mov_b32_e32 v89, v0
	v_mov_b32_e32 v98, v0
	v_mov_b32_e32 v99, v0
	v_mov_b32_e32 v100, v0
	v_mov_b32_e32 v101, v0
	v_mov_b32_e32 v102, v0
	v_mov_b32_e32 v103, v0
	v_mov_b32_e32 v104, v0
	v_mov_b32_e32 v105, v0
	v_mov_b32_e32 v114, v0
	v_mov_b32_e32 v115, v0
	v_mov_b32_e32 v116, v0
	v_mov_b32_e32 v117, v0
	v_mov_b32_e32 v118, v0
	v_mov_b32_e32 v119, v0
	v_mov_b32_e32 v120, v0
	v_mov_b32_e32 v121, v0
	v_mov_b32_e32 v74, v0
	v_mov_b32_e32 v75, v0
	v_mov_b32_e32 v76, v0
	v_mov_b32_e32 v77, v0
	v_mov_b32_e32 v78, v0
	v_mov_b32_e32 v79, v0
	v_mov_b32_e32 v80, v0
	v_mov_b32_e32 v81, v0
	v_mov_b32_e32 v90, v0
	v_mov_b32_e32 v91, v0
	v_mov_b32_e32 v92, v0
	v_mov_b32_e32 v93, v0
	v_mov_b32_e32 v94, v0
	v_mov_b32_e32 v95, v0
	v_mov_b32_e32 v96, v0
	v_mov_b32_e32 v97, v0
	v_mov_b32_e32 v106, v0
	v_mov_b32_e32 v107, v0
	v_mov_b32_e32 v108, v0
	v_mov_b32_e32 v109, v0
	v_mov_b32_e32 v110, v0
	v_mov_b32_e32 v111, v0
	v_mov_b32_e32 v112, v0
	v_mov_b32_e32 v113, v0
	v_mov_b32_e32 v122, v0
	v_mov_b32_e32 v123, v0
	v_mov_b32_e32 v124, v0
	v_mov_b32_e32 v125, v0
	v_mov_b32_e32 v126, v0
	v_mov_b32_e32 v127, v0
	v_mov_b32_e32 v128, v0
	v_mov_b32_e32 v129, v0
	s_cmp_eq_u32 s36, 1
	s_cbranch_scc1 .LBB0_81
	s_add_u32 s14, s0, 0x100
	s_addc_u32 s15, s1, 0
	s_add_i32 s3, 0, 0x10000
	s_cmpk_eq_i32 s9, 0x7c
	s_cselect_b32 s27, s43, s15
	s_cselect_b32 s26, s42, s14
	v_add_u32_e32 v162, s3, v145
	s_cselect_b32 s23, s79, s8
	s_cselect_b32 s22, s78, s2
	s_add_i32 s4, 0, 0x14000
	ds_read_b128 v[140:143], v162
	ds_read_b128 v[148:151], v162 offset:1024
	ds_read_b128 v[172:175], v162 offset:2048
	ds_read_b128 v[190:193], v162 offset:3072
	v_add_u32_e32 v162, s4, v145
	ds_read_b128 v[194:197], v162
	ds_read_b128 v[198:201], v162 offset:1024
	ds_read_b128 v[202:205], v162 offset:2048
	ds_read_b128 v[206:209], v162 offset:3072
	v_lshl_add_u64 v[162:163], s[0:1], 0, v[136:137]
	s_add_i32 m0, s30, 0xc000
	ds_read_b128 v[210:213], v147
	ds_read_b128 v[214:217], v147 offset:1024
	ds_read_b128 v[218:221], v147 offset:2048
	ds_read_b128 v[222:225], v147 offset:3072
	ds_read_b128 v[226:229], v147 offset:4096
	ds_read_b128 v[230:233], v147 offset:5120
	ds_read_b128 v[234:237], v147 offset:6144
	ds_read_b128 v[238:241], v147 offset:7168
	global_load_lds_dwordx4 v[162:163], off
	v_lshl_add_u64 v[162:163], s[0:1], 0, v[138:139]
	s_add_i32 m0, s30, 0xe000
	s_nop 0
	global_load_lds_dwordx4 v[162:163], off
	s_waitcnt vmcnt(32)
	s_waitcnt lgkmcnt(0)
	s_barrier
	s_setprio 1
	s_waitcnt lgkmcnt(0)
	v_mfma_f32_16x16x32_bf16 v[126:129], v[140:143], v[210:213], v[126:129]
	v_mfma_f32_16x16x32_bf16 v[122:125], v[172:175], v[210:213], v[122:125]
	v_mfma_f32_16x16x32_bf16 v[110:113], v[140:143], v[218:221], v[110:113]
	v_mfma_f32_16x16x32_bf16 v[106:109], v[172:175], v[218:221], v[106:109]
	v_mfma_f32_16x16x32_bf16 v[94:97], v[140:143], v[226:229], v[94:97]
	v_mfma_f32_16x16x32_bf16 v[90:93], v[172:175], v[226:229], v[90:93]
	v_mfma_f32_16x16x32_bf16 v[78:81], v[140:143], v[234:237], v[78:81]
	v_mfma_f32_16x16x32_bf16 v[74:77], v[172:175], v[234:237], v[74:77]
	v_mfma_f32_16x16x32_bf16 v[126:129], v[148:151], v[214:217], v[126:129]
	v_mfma_f32_16x16x32_bf16 v[122:125], v[190:193], v[214:217], v[122:125]
	v_mfma_f32_16x16x32_bf16 v[110:113], v[148:151], v[222:225], v[110:113]
	v_mfma_f32_16x16x32_bf16 v[106:109], v[190:193], v[222:225], v[106:109]
	v_mfma_f32_16x16x32_bf16 v[94:97], v[148:151], v[230:233], v[94:97]
	v_mfma_f32_16x16x32_bf16 v[90:93], v[190:193], v[230:233], v[90:93]
	v_mfma_f32_16x16x32_bf16 v[78:81], v[148:151], v[238:241], v[78:81]
	v_mfma_f32_16x16x32_bf16 v[74:77], v[190:193], v[238:241], v[74:77]
	s_setprio 0
	s_setprio 1
	v_mfma_f32_16x16x32_bf16 v[118:121], v[194:197], v[210:213], v[118:121]
	v_mfma_f32_16x16x32_bf16 v[114:117], v[202:205], v[210:213], v[114:117]
	v_mfma_f32_16x16x32_bf16 v[102:105], v[194:197], v[218:221], v[102:105]
	v_mfma_f32_16x16x32_bf16 v[98:101], v[202:205], v[218:221], v[98:101]
	v_mfma_f32_16x16x32_bf16 v[86:89], v[194:197], v[226:229], v[86:89]
	v_mfma_f32_16x16x32_bf16 v[82:85], v[202:205], v[226:229], v[82:85]
	v_mfma_f32_16x16x32_bf16 v[70:73], v[194:197], v[234:237], v[70:73]
	v_mfma_f32_16x16x32_bf16 v[66:69], v[202:205], v[234:237], v[66:69]
	v_mfma_f32_16x16x32_bf16 v[118:121], v[198:201], v[214:217], v[118:121]
	v_mfma_f32_16x16x32_bf16 v[114:117], v[206:209], v[214:217], v[114:117]
	v_mfma_f32_16x16x32_bf16 v[102:105], v[198:201], v[222:225], v[102:105]
	v_mfma_f32_16x16x32_bf16 v[98:101], v[206:209], v[222:225], v[98:101]
	v_mfma_f32_16x16x32_bf16 v[86:89], v[198:201], v[230:233], v[86:89]
	v_mfma_f32_16x16x32_bf16 v[82:85], v[206:209], v[230:233], v[82:85]
	v_mfma_f32_16x16x32_bf16 v[70:73], v[198:201], v[238:241], v[70:73]
	v_mfma_f32_16x16x32_bf16 v[66:69], v[206:209], v[238:241], v[66:69]
	s_setprio 0
	s_barrier
	s_add_i32 s0, s3, s11
	v_lshl_add_u64 v[162:163], s[22:23], 0, v[4:5]
	s_mov_b32 m0, s0
	ds_read_b128 v[210:213], v147 offset:16384
	ds_read_b128 v[214:217], v147 offset:17408
	ds_read_b128 v[218:221], v147 offset:18432
	ds_read_b128 v[222:225], v147 offset:19456
	ds_read_b128 v[226:229], v147 offset:20480
	ds_read_b128 v[230:233], v147 offset:21504
	ds_read_b128 v[234:237], v147 offset:22528
	ds_read_b128 v[238:241], v147 offset:23552
	global_load_lds_dwordx4 v[162:163], off
	s_add_i32 m0, s0, 0x2000
	s_add_u32 s0, s22, 0x208000
	v_lshl_add_u64 v[166:167], s[22:23], 0, v[130:131]
	s_addc_u32 s1, s23, 0
	s_add_i32 s3, s4, s11
	global_load_lds_dwordx4 v[166:167], off
	v_lshl_add_u64 v[176:177], s[0:1], 0, v[4:5]
	s_mov_b32 m0, s3
	v_lshl_add_u64 v[180:181], s[26:27], 0, v[132:133]
	global_load_lds_dwordx4 v[176:177], off
	v_lshl_add_u64 v[176:177], s[0:1], 0, v[130:131]
	s_add_i32 m0, s3, 0x2000
	s_nop 0
	global_load_lds_dwordx4 v[176:177], off
	v_lshl_add_u64 v[176:177], s[26:27], 0, v[134:135]
	s_mov_b32 m0, s30
	s_nop 0
	global_load_lds_dwordx4 v[176:177], off
	s_mov_b32 m0, s31
	s_nop 0
	global_load_lds_dwordx4 v[180:181], off
	s_waitcnt vmcnt(32)
	s_waitcnt lgkmcnt(0)
	s_barrier
	s_setprio 1
	s_waitcnt lgkmcnt(0)
	v_mfma_f32_16x16x32_bf16 v[62:65], v[140:143], v[210:213], v[62:65]
	v_mfma_f32_16x16x32_bf16 v[58:61], v[172:175], v[210:213], v[58:61]
	v_mfma_f32_16x16x32_bf16 v[46:49], v[140:143], v[218:221], v[46:49]
	v_mfma_f32_16x16x32_bf16 v[42:45], v[172:175], v[218:221], v[42:45]
	v_mfma_f32_16x16x32_bf16 v[30:33], v[140:143], v[226:229], v[30:33]
	v_mfma_f32_16x16x32_bf16 v[26:29], v[172:175], v[226:229], v[26:29]
	v_mfma_f32_16x16x32_bf16 v[14:17], v[140:143], v[234:237], v[14:17]
	v_mfma_f32_16x16x32_bf16 v[10:13], v[172:175], v[234:237], v[10:13]
	v_mfma_f32_16x16x32_bf16 v[62:65], v[148:151], v[214:217], v[62:65]
	v_mfma_f32_16x16x32_bf16 v[58:61], v[190:193], v[214:217], v[58:61]
	v_mfma_f32_16x16x32_bf16 v[46:49], v[148:151], v[222:225], v[46:49]
	v_mfma_f32_16x16x32_bf16 v[42:45], v[190:193], v[222:225], v[42:45]
	v_mfma_f32_16x16x32_bf16 v[30:33], v[148:151], v[230:233], v[30:33]
	v_mfma_f32_16x16x32_bf16 v[26:29], v[190:193], v[230:233], v[26:29]
	v_mfma_f32_16x16x32_bf16 v[14:17], v[148:151], v[238:241], v[14:17]
	v_mfma_f32_16x16x32_bf16 v[10:13], v[190:193], v[238:241], v[10:13]
	s_setprio 0
	s_setprio 1
	v_mfma_f32_16x16x32_bf16 v[54:57], v[194:197], v[210:213], v[54:57]
	v_mfma_f32_16x16x32_bf16 v[50:53], v[202:205], v[210:213], v[50:53]
	v_mfma_f32_16x16x32_bf16 v[38:41], v[194:197], v[218:221], v[38:41]
	v_mfma_f32_16x16x32_bf16 v[34:37], v[202:205], v[218:221], v[34:37]
	v_mfma_f32_16x16x32_bf16 v[22:25], v[194:197], v[226:229], v[22:25]
	v_mfma_f32_16x16x32_bf16 v[18:21], v[202:205], v[226:229], v[18:21]
	v_mfma_f32_16x16x32_bf16 v[6:9], v[194:197], v[234:237], v[6:9]
	v_mfma_f32_16x16x32_bf16 v[0:3], v[202:205], v[234:237], v[0:3]
	v_mfma_f32_16x16x32_bf16 v[54:57], v[198:201], v[214:217], v[54:57]
	v_mfma_f32_16x16x32_bf16 v[50:53], v[206:209], v[214:217], v[50:53]
	v_mfma_f32_16x16x32_bf16 v[38:41], v[198:201], v[222:225], v[38:41]
	v_mfma_f32_16x16x32_bf16 v[34:37], v[206:209], v[222:225], v[34:37]
	v_mfma_f32_16x16x32_bf16 v[22:25], v[198:201], v[230:233], v[22:25]
	v_mfma_f32_16x16x32_bf16 v[18:21], v[206:209], v[230:233], v[18:21]
	v_mfma_f32_16x16x32_bf16 v[6:9], v[198:201], v[238:241], v[6:9]
	v_mfma_f32_16x16x32_bf16 v[0:3], v[206:209], v[238:241], v[0:3]
	s_setprio 0
	s_barrier
	s_branch .Lpeelmid_81

.LBB0_162:
	s_ashr_i32 s49, s48, 31
	s_lshl_b64 s[2:3], s[48:49], 20
	v_readlane_b32 s4, v253, 61
	v_readlane_b32 s5, v253, 62
	s_add_u32 s82, s4, s2
	s_addc_u32 s83, s5, s3
	s_and_b64 s[2:3], s[42:43], exec
	s_cselect_b32 s2, s83, s1
	s_cselect_b32 s8, s82, s0
	s_add_u32 s22, s14, 0x80080
	s_addc_u32 s23, s15, 0
	s_add_u32 s9, s0, 0x100
	v_mov_b32_e32 v0, 0
	s_addc_u32 s10, s1, 0
	s_mov_b32 s24, -2
	v_mov_b32_e32 v1, v0
	v_mov_b32_e32 v2, v0
	v_mov_b32_e32 v3, v0
	v_mov_b32_e32 v6, v0
	s_waitcnt lgkmcnt(0)
	v_mov_b32_e32 v7, v0
	v_mov_b32_e32 v8, v0
	v_mov_b32_e32 v9, v0
	v_mov_b32_e32 v18, v0
	v_mov_b32_e32 v19, v0
	v_mov_b32_e32 v20, v0
	v_mov_b32_e32 v21, v0
	v_mov_b32_e32 v22, v0
	v_mov_b32_e32 v23, v0
	v_mov_b32_e32 v24, v0
	v_mov_b32_e32 v25, v0
	v_mov_b32_e32 v34, v0
	v_mov_b32_e32 v35, v0
	v_mov_b32_e32 v36, v0
	v_mov_b32_e32 v37, v0
	v_mov_b32_e32 v38, v0
	v_mov_b32_e32 v39, v0
	v_mov_b32_e32 v40, v0
	v_mov_b32_e32 v41, v0
	v_mov_b32_e32 v50, v0
	v_mov_b32_e32 v51, v0
	v_mov_b32_e32 v52, v0
	v_mov_b32_e32 v53, v0
	v_mov_b32_e32 v54, v0
	v_mov_b32_e32 v55, v0
	v_mov_b32_e32 v56, v0
	v_mov_b32_e32 v57, v0
	v_mov_b32_e32 v10, v0
	v_mov_b32_e32 v11, v0
	v_mov_b32_e32 v12, v0
	v_mov_b32_e32 v13, v0
	v_mov_b32_e32 v14, v0
	v_mov_b32_e32 v15, v0
	v_mov_b32_e32 v16, v0
	v_mov_b32_e32 v17, v0
	v_mov_b32_e32 v26, v0
	v_mov_b32_e32 v27, v0
	v_mov_b32_e32 v28, v0
	v_mov_b32_e32 v29, v0
	v_mov_b32_e32 v30, v0
	v_mov_b32_e32 v31, v0
	v_mov_b32_e32 v32, v0
	v_mov_b32_e32 v33, v0
	v_mov_b32_e32 v42, v0
	v_mov_b32_e32 v43, v0
	v_mov_b32_e32 v44, v0
	v_mov_b32_e32 v45, v0
	v_mov_b32_e32 v46, v0
	v_mov_b32_e32 v47, v0
	v_mov_b32_e32 v48, v0
	v_mov_b32_e32 v49, v0
	v_mov_b32_e32 v58, v0
	v_mov_b32_e32 v59, v0
	v_mov_b32_e32 v60, v0
	v_mov_b32_e32 v61, v0
	v_mov_b32_e32 v62, v0
	v_mov_b32_e32 v63, v0
	v_mov_b32_e32 v64, v0
	v_mov_b32_e32 v65, v0
	v_mov_b32_e32 v66, v0
	v_mov_b32_e32 v67, v0
	v_mov_b32_e32 v68, v0
	v_mov_b32_e32 v69, v0
	v_mov_b32_e32 v70, v0
	v_mov_b32_e32 v71, v0
	v_mov_b32_e32 v72, v0
	v_mov_b32_e32 v73, v0
	v_mov_b32_e32 v82, v0
	v_mov_b32_e32 v83, v0
	v_mov_b32_e32 v84, v0
	v_mov_b32_e32 v85, v0
	v_mov_b32_e32 v86, v0
	v_mov_b32_e32 v87, v0
	v_mov_b32_e32 v88, v0
	v_mov_b32_e32 v89, v0
	v_mov_b32_e32 v98, v0
	v_mov_b32_e32 v99, v0
	v_mov_b32_e32 v100, v0
	v_mov_b32_e32 v101, v0
	v_mov_b32_e32 v102, v0
	v_mov_b32_e32 v103, v0
	v_mov_b32_e32 v104, v0
	v_mov_b32_e32 v105, v0
	v_mov_b32_e32 v114, v0
	v_mov_b32_e32 v115, v0
	v_mov_b32_e32 v116, v0
	v_mov_b32_e32 v117, v0
	v_mov_b32_e32 v118, v0
	v_mov_b32_e32 v119, v0
	v_mov_b32_e32 v120, v0
	v_mov_b32_e32 v121, v0
	v_mov_b32_e32 v74, v0
	v_mov_b32_e32 v75, v0
	v_mov_b32_e32 v76, v0
	v_mov_b32_e32 v77, v0
	v_mov_b32_e32 v78, v0
	v_mov_b32_e32 v79, v0
	v_mov_b32_e32 v80, v0
	v_mov_b32_e32 v81, v0
	v_mov_b32_e32 v90, v0
	v_mov_b32_e32 v91, v0
	v_mov_b32_e32 v92, v0
	v_mov_b32_e32 v93, v0
	v_mov_b32_e32 v94, v0
	v_mov_b32_e32 v95, v0
	v_mov_b32_e32 v96, v0
	v_mov_b32_e32 v97, v0
	v_mov_b32_e32 v106, v0
	v_mov_b32_e32 v107, v0
	v_mov_b32_e32 v108, v0
	v_mov_b32_e32 v109, v0
	v_mov_b32_e32 v110, v0
	v_mov_b32_e32 v111, v0
	v_mov_b32_e32 v112, v0
	v_mov_b32_e32 v113, v0
	v_mov_b32_e32 v122, v0
	v_mov_b32_e32 v123, v0
	v_mov_b32_e32 v124, v0
	v_mov_b32_e32 v125, v0
	v_mov_b32_e32 v126, v0
	v_mov_b32_e32 v127, v0
	v_mov_b32_e32 v128, v0
	v_mov_b32_e32 v129, v0
	s_cmp_eq_u32 s37, 1
	s_cbranch_scc1 .LBB0_163
	s_add_u32 s0, s22, 0xfff80080
	s_addc_u32 s1, s23, -1
	s_add_i32 s3, 0, 0x10000
	s_cmp_eq_u32 s24, 28
	s_cselect_b32 s15, s79, s1
	s_cselect_b32 s14, s78, s0
	v_add_u32_e32 v162, s3, v145
	s_cselect_b32 s1, s2, s10
	s_cselect_b32 s0, s8, s9
	s_add_i32 s6, 0, 0x14000
	ds_read_b128 v[140:143], v162
	ds_read_b128 v[148:151], v162 offset:1024
	ds_read_b128 v[172:175], v162 offset:2048
	ds_read_b128 v[190:193], v162 offset:3072
	v_add_u32_e32 v162, s6, v145
	ds_read_b128 v[194:197], v162
	ds_read_b128 v[198:201], v162 offset:1024
	ds_read_b128 v[202:205], v162 offset:2048
	ds_read_b128 v[206:209], v162 offset:3072
	v_lshl_add_u64 v[162:163], s[22:23], 0, v[136:137]
	s_add_i32 m0, s26, 0xc000
	ds_read_b128 v[210:213], v147
	ds_read_b128 v[214:217], v147 offset:1024
	ds_read_b128 v[218:221], v147 offset:2048
	ds_read_b128 v[222:225], v147 offset:3072
	ds_read_b128 v[226:229], v147 offset:4096
	ds_read_b128 v[230:233], v147 offset:5120
	ds_read_b128 v[234:237], v147 offset:6144
	ds_read_b128 v[238:241], v147 offset:7168
	global_load_lds_dwordx4 v[162:163], off
	v_lshl_add_u64 v[162:163], s[22:23], 0, v[138:139]
	s_add_i32 m0, s26, 0xe000
	s_nop 0
	global_load_lds_dwordx4 v[162:163], off
	s_waitcnt vmcnt(32)
	s_waitcnt lgkmcnt(0)
	s_barrier
	s_setprio 1
	s_waitcnt lgkmcnt(0)
	v_mfma_f32_16x16x32_bf16 v[126:129], v[140:143], v[210:213], v[126:129]
	v_mfma_f32_16x16x32_bf16 v[122:125], v[172:175], v[210:213], v[122:125]
	v_mfma_f32_16x16x32_bf16 v[110:113], v[140:143], v[218:221], v[110:113]
	v_mfma_f32_16x16x32_bf16 v[106:109], v[172:175], v[218:221], v[106:109]
	v_mfma_f32_16x16x32_bf16 v[94:97], v[140:143], v[226:229], v[94:97]
	v_mfma_f32_16x16x32_bf16 v[90:93], v[172:175], v[226:229], v[90:93]
	v_mfma_f32_16x16x32_bf16 v[78:81], v[140:143], v[234:237], v[78:81]
	v_mfma_f32_16x16x32_bf16 v[74:77], v[172:175], v[234:237], v[74:77]
	v_mfma_f32_16x16x32_bf16 v[126:129], v[148:151], v[214:217], v[126:129]
	v_mfma_f32_16x16x32_bf16 v[122:125], v[190:193], v[214:217], v[122:125]
	v_mfma_f32_16x16x32_bf16 v[110:113], v[148:151], v[222:225], v[110:113]
	v_mfma_f32_16x16x32_bf16 v[106:109], v[190:193], v[222:225], v[106:109]
	v_mfma_f32_16x16x32_bf16 v[94:97], v[148:151], v[230:233], v[94:97]
	v_mfma_f32_16x16x32_bf16 v[90:93], v[190:193], v[230:233], v[90:93]
	v_mfma_f32_16x16x32_bf16 v[78:81], v[148:151], v[238:241], v[78:81]
	v_mfma_f32_16x16x32_bf16 v[74:77], v[190:193], v[238:241], v[74:77]
	s_setprio 0
	s_setprio 1
	v_mfma_f32_16x16x32_bf16 v[118:121], v[194:197], v[210:213], v[118:121]
	v_mfma_f32_16x16x32_bf16 v[114:117], v[202:205], v[210:213], v[114:117]
	v_mfma_f32_16x16x32_bf16 v[102:105], v[194:197], v[218:221], v[102:105]
	v_mfma_f32_16x16x32_bf16 v[98:101], v[202:205], v[218:221], v[98:101]
	v_mfma_f32_16x16x32_bf16 v[86:89], v[194:197], v[226:229], v[86:89]
	v_mfma_f32_16x16x32_bf16 v[82:85], v[202:205], v[226:229], v[82:85]
	v_mfma_f32_16x16x32_bf16 v[70:73], v[194:197], v[234:237], v[70:73]
	v_mfma_f32_16x16x32_bf16 v[66:69], v[202:205], v[234:237], v[66:69]
	v_mfma_f32_16x16x32_bf16 v[118:121], v[198:201], v[214:217], v[118:121]
	v_mfma_f32_16x16x32_bf16 v[114:117], v[206:209], v[214:217], v[114:117]
	v_mfma_f32_16x16x32_bf16 v[102:105], v[198:201], v[222:225], v[102:105]
	v_mfma_f32_16x16x32_bf16 v[98:101], v[206:209], v[222:225], v[98:101]
	v_mfma_f32_16x16x32_bf16 v[86:89], v[198:201], v[230:233], v[86:89]
	v_mfma_f32_16x16x32_bf16 v[82:85], v[206:209], v[230:233], v[82:85]
	v_mfma_f32_16x16x32_bf16 v[70:73], v[198:201], v[238:241], v[70:73]
	v_mfma_f32_16x16x32_bf16 v[66:69], v[206:209], v[238:241], v[66:69]
	s_setprio 0
	s_barrier
	s_add_i32 s3, s3, s11
	v_lshl_add_u64 v[162:163], s[0:1], 0, v[4:5]
	s_mov_b32 m0, s3
	ds_read_b128 v[210:213], v147 offset:16384
	ds_read_b128 v[214:217], v147 offset:17408
	ds_read_b128 v[218:221], v147 offset:18432
	ds_read_b128 v[222:225], v147 offset:19456
	ds_read_b128 v[226:229], v147 offset:20480
	ds_read_b128 v[230:233], v147 offset:21504
	ds_read_b128 v[234:237], v147 offset:22528
	ds_read_b128 v[238:241], v147 offset:23552
	global_load_lds_dwordx4 v[162:163], off
	s_add_i32 m0, s3, 0x2000
	s_add_u32 s4, s0, 0x80000
	v_lshl_add_u64 v[166:167], s[0:1], 0, v[130:131]
	s_addc_u32 s5, s1, 0
	s_add_i32 s3, s6, s11
	global_load_lds_dwordx4 v[166:167], off
	v_lshl_add_u64 v[176:177], s[4:5], 0, v[4:5]
	s_mov_b32 m0, s3
	v_lshl_add_u64 v[180:181], s[14:15], 0, v[132:133]
	global_load_lds_dwordx4 v[176:177], off
	v_lshl_add_u64 v[176:177], s[4:5], 0, v[130:131]
	s_add_i32 m0, s3, 0x2000
	s_nop 0
	global_load_lds_dwordx4 v[176:177], off
	v_lshl_add_u64 v[176:177], s[14:15], 0, v[134:135]
	s_mov_b32 m0, s26
	s_nop 0
	global_load_lds_dwordx4 v[176:177], off
	s_mov_b32 m0, s27
	s_nop 0
	global_load_lds_dwordx4 v[180:181], off
	s_waitcnt vmcnt(32)
	s_waitcnt lgkmcnt(0)
	s_barrier
	s_setprio 1
	s_waitcnt lgkmcnt(0)
	v_mfma_f32_16x16x32_bf16 v[62:65], v[140:143], v[210:213], v[62:65]
	v_mfma_f32_16x16x32_bf16 v[58:61], v[172:175], v[210:213], v[58:61]
	v_mfma_f32_16x16x32_bf16 v[46:49], v[140:143], v[218:221], v[46:49]
	v_mfma_f32_16x16x32_bf16 v[42:45], v[172:175], v[218:221], v[42:45]
	v_mfma_f32_16x16x32_bf16 v[30:33], v[140:143], v[226:229], v[30:33]
	v_mfma_f32_16x16x32_bf16 v[26:29], v[172:175], v[226:229], v[26:29]
	v_mfma_f32_16x16x32_bf16 v[14:17], v[140:143], v[234:237], v[14:17]
	v_mfma_f32_16x16x32_bf16 v[10:13], v[172:175], v[234:237], v[10:13]
	v_mfma_f32_16x16x32_bf16 v[62:65], v[148:151], v[214:217], v[62:65]
	v_mfma_f32_16x16x32_bf16 v[58:61], v[190:193], v[214:217], v[58:61]
	v_mfma_f32_16x16x32_bf16 v[46:49], v[148:151], v[222:225], v[46:49]
	v_mfma_f32_16x16x32_bf16 v[42:45], v[190:193], v[222:225], v[42:45]
	v_mfma_f32_16x16x32_bf16 v[30:33], v[148:151], v[230:233], v[30:33]
	v_mfma_f32_16x16x32_bf16 v[26:29], v[190:193], v[230:233], v[26:29]
	v_mfma_f32_16x16x32_bf16 v[14:17], v[148:151], v[238:241], v[14:17]
	v_mfma_f32_16x16x32_bf16 v[10:13], v[190:193], v[238:241], v[10:13]
	s_setprio 0
	s_setprio 1
	v_mfma_f32_16x16x32_bf16 v[54:57], v[194:197], v[210:213], v[54:57]
	v_mfma_f32_16x16x32_bf16 v[50:53], v[202:205], v[210:213], v[50:53]
	v_mfma_f32_16x16x32_bf16 v[38:41], v[194:197], v[218:221], v[38:41]
	v_mfma_f32_16x16x32_bf16 v[34:37], v[202:205], v[218:221], v[34:37]
	v_mfma_f32_16x16x32_bf16 v[22:25], v[194:197], v[226:229], v[22:25]
	v_mfma_f32_16x16x32_bf16 v[18:21], v[202:205], v[226:229], v[18:21]
	v_mfma_f32_16x16x32_bf16 v[6:9], v[194:197], v[234:237], v[6:9]
	v_mfma_f32_16x16x32_bf16 v[0:3], v[202:205], v[234:237], v[0:3]
	v_mfma_f32_16x16x32_bf16 v[54:57], v[198:201], v[214:217], v[54:57]
	v_mfma_f32_16x16x32_bf16 v[50:53], v[206:209], v[214:217], v[50:53]
	v_mfma_f32_16x16x32_bf16 v[38:41], v[198:201], v[222:225], v[38:41]
	v_mfma_f32_16x16x32_bf16 v[34:37], v[206:209], v[222:225], v[34:37]
	v_mfma_f32_16x16x32_bf16 v[22:25], v[198:201], v[230:233], v[22:25]
	v_mfma_f32_16x16x32_bf16 v[18:21], v[206:209], v[230:233], v[18:21]
	v_mfma_f32_16x16x32_bf16 v[6:9], v[198:201], v[238:241], v[6:9]
	v_mfma_f32_16x16x32_bf16 v[0:3], v[206:209], v[238:241], v[0:3]
	s_setprio 0
	s_barrier
	s_branch .Lpeelmid_163

.LBB0_204:
	s_ashr_i32 s49, s48, 31
	s_lshl_b64 s[2:3], s[48:49], 19
	v_readlane_b32 s4, v253, 17
	v_readlane_b32 s5, v253, 18
	s_add_u32 s84, s4, s2
	s_addc_u32 s85, s5, s3
	s_and_b64 s[2:3], s[42:43], exec
	s_cselect_b32 s2, s85, s15
	s_cselect_b32 s8, s84, s14
	s_add_u32 s22, s0, 0x40080
	s_addc_u32 s23, s1, 0
	s_add_u32 s9, s14, 0x100
	v_mov_b32_e32 v0, 0
	s_addc_u32 s10, s15, 0
	s_mov_b32 s24, -2
	v_mov_b32_e32 v1, v0
	v_mov_b32_e32 v2, v0
	v_mov_b32_e32 v3, v0
	v_mov_b32_e32 v6, v0
	v_mov_b32_e32 v7, v0
	v_mov_b32_e32 v8, v0
	v_mov_b32_e32 v9, v0
	v_mov_b32_e32 v10, v0
	v_mov_b32_e32 v11, v0
	v_mov_b32_e32 v12, v0
	v_mov_b32_e32 v13, v0
	v_mov_b32_e32 v14, v0
	v_mov_b32_e32 v15, v0
	v_mov_b32_e32 v16, v0
	v_mov_b32_e32 v17, v0
	v_mov_b32_e32 v18, v0
	v_mov_b32_e32 v19, v0
	v_mov_b32_e32 v20, v0
	v_mov_b32_e32 v21, v0
	v_mov_b32_e32 v22, v0
	v_mov_b32_e32 v23, v0
	v_mov_b32_e32 v24, v0
	v_mov_b32_e32 v25, v0
	v_mov_b32_e32 v26, v0
	v_mov_b32_e32 v27, v0
	v_mov_b32_e32 v28, v0
	v_mov_b32_e32 v29, v0
	v_mov_b32_e32 v30, v0
	v_mov_b32_e32 v31, v0
	v_mov_b32_e32 v32, v0
	v_mov_b32_e32 v33, v0
	v_mov_b32_e32 v66, v0
	v_mov_b32_e32 v67, v0
	v_mov_b32_e32 v68, v0
	v_mov_b32_e32 v69, v0
	v_mov_b32_e32 v70, v0
	v_mov_b32_e32 v71, v0
	v_mov_b32_e32 v72, v0
	v_mov_b32_e32 v73, v0
	v_mov_b32_e32 v74, v0
	v_mov_b32_e32 v75, v0
	v_mov_b32_e32 v76, v0
	v_mov_b32_e32 v77, v0
	v_mov_b32_e32 v78, v0
	v_mov_b32_e32 v79, v0
	v_mov_b32_e32 v80, v0
	v_mov_b32_e32 v81, v0
	v_mov_b32_e32 v82, v0
	v_mov_b32_e32 v83, v0
	v_mov_b32_e32 v84, v0
	v_mov_b32_e32 v85, v0
	v_mov_b32_e32 v86, v0
	v_mov_b32_e32 v87, v0
	v_mov_b32_e32 v88, v0
	v_mov_b32_e32 v89, v0
	v_mov_b32_e32 v90, v0
	v_mov_b32_e32 v91, v0
	v_mov_b32_e32 v92, v0
	v_mov_b32_e32 v93, v0
	v_mov_b32_e32 v94, v0
	v_mov_b32_e32 v95, v0
	v_mov_b32_e32 v96, v0
	v_mov_b32_e32 v97, v0
	v_mov_b32_e32 v34, v0
	v_mov_b32_e32 v35, v0
	v_mov_b32_e32 v36, v0
	v_mov_b32_e32 v37, v0
	v_mov_b32_e32 v38, v0
	v_mov_b32_e32 v39, v0
	v_mov_b32_e32 v40, v0
	v_mov_b32_e32 v41, v0
	v_mov_b32_e32 v42, v0
	v_mov_b32_e32 v43, v0
	v_mov_b32_e32 v44, v0
	v_mov_b32_e32 v45, v0
	v_mov_b32_e32 v46, v0
	v_mov_b32_e32 v47, v0
	v_mov_b32_e32 v48, v0
	v_mov_b32_e32 v49, v0
	v_mov_b32_e32 v50, v0
	v_mov_b32_e32 v51, v0
	v_mov_b32_e32 v52, v0
	v_mov_b32_e32 v53, v0
	v_mov_b32_e32 v54, v0
	v_mov_b32_e32 v55, v0
	v_mov_b32_e32 v56, v0
	v_mov_b32_e32 v57, v0
	v_mov_b32_e32 v58, v0
	v_mov_b32_e32 v59, v0
	v_mov_b32_e32 v60, v0
	v_mov_b32_e32 v61, v0
	v_mov_b32_e32 v62, v0
	v_mov_b32_e32 v63, v0
	v_mov_b32_e32 v64, v0
	v_mov_b32_e32 v65, v0
	v_mov_b32_e32 v98, v0
	v_mov_b32_e32 v99, v0
	v_mov_b32_e32 v100, v0
	v_mov_b32_e32 v101, v0
	v_mov_b32_e32 v102, v0
	v_mov_b32_e32 v103, v0
	v_mov_b32_e32 v104, v0
	v_mov_b32_e32 v105, v0
	v_mov_b32_e32 v106, v0
	v_mov_b32_e32 v107, v0
	v_mov_b32_e32 v108, v0
	v_mov_b32_e32 v109, v0
	v_mov_b32_e32 v110, v0
	v_mov_b32_e32 v111, v0
	v_mov_b32_e32 v112, v0
	v_mov_b32_e32 v113, v0
	v_mov_b32_e32 v114, v0
	v_mov_b32_e32 v115, v0
	v_mov_b32_e32 v116, v0
	v_mov_b32_e32 v117, v0
	v_mov_b32_e32 v118, v0
	v_mov_b32_e32 v119, v0
	v_mov_b32_e32 v120, v0
	v_mov_b32_e32 v121, v0
	v_mov_b32_e32 v122, v0
	v_mov_b32_e32 v123, v0
	v_mov_b32_e32 v124, v0
	v_mov_b32_e32 v125, v0
	v_mov_b32_e32 v126, v0
	v_mov_b32_e32 v127, v0
	v_mov_b32_e32 v128, v0
	v_mov_b32_e32 v129, v0
	s_cmp_eq_u32 s37, 1
	s_cbranch_scc1 .LBB0_205
	s_add_u32 s0, s22, 0xfffc0080
	s_addc_u32 s1, s23, -1
	s_add_i32 s3, 0, 0x10000
	s_cmp_eq_u32 s24, 12
	s_cselect_b32 s15, s83, s1
	s_cselect_b32 s14, s82, s0
	v_add_u32_e32 v144, s3, v168
	s_cselect_b32 s1, s2, s10
	s_cselect_b32 s0, s8, s9
	s_add_i32 s6, 0, 0x14000
	ds_read_b128 v[140:143], v144
	ds_read_b128 v[174:177], v144 offset:1024
	ds_read_b128 v[190:193], v144 offset:2048
	ds_read_b128 v[194:197], v144 offset:3072
	v_add_u32_e32 v144, s6, v168
	ds_read_b128 v[198:201], v144
	ds_read_b128 v[202:205], v144 offset:1024
	ds_read_b128 v[206:209], v144 offset:2048
	ds_read_b128 v[210:213], v144 offset:3072
	v_lshl_add_u64 v[144:145], s[22:23], 0, v[136:137]
	s_add_i32 m0, s27, 0xc000
	ds_read_b128 v[214:217], v172
	ds_read_b128 v[218:221], v172 offset:1024
	ds_read_b128 v[222:225], v172 offset:2048
	ds_read_b128 v[226:229], v172 offset:3072
	ds_read_b128 v[230:233], v172 offset:4096
	ds_read_b128 v[234:237], v172 offset:5120
	ds_read_b128 v[238:241], v172 offset:6144
	ds_read_b128 v[242:245], v172 offset:7168
	global_load_lds_dwordx4 v[144:145], off
	v_lshl_add_u64 v[144:145], s[22:23], 0, v[138:139]
	s_add_i32 m0, s27, 0xe000
	s_nop 0
	global_load_lds_dwordx4 v[144:145], off
	s_waitcnt vmcnt(40)
	s_waitcnt lgkmcnt(0)
	s_barrier
	s_setprio 1
	s_waitcnt lgkmcnt(0)
	v_mfma_f32_16x16x32_bf16 v[126:129], v[140:143], v[214:217], v[126:129]
	v_mfma_f32_16x16x32_bf16 v[122:125], v[190:193], v[214:217], v[122:125]
	v_mfma_f32_16x16x32_bf16 v[118:121], v[140:143], v[222:225], v[118:121]
	v_mfma_f32_16x16x32_bf16 v[114:117], v[190:193], v[222:225], v[114:117]
	v_mfma_f32_16x16x32_bf16 v[110:113], v[140:143], v[230:233], v[110:113]
	v_mfma_f32_16x16x32_bf16 v[106:109], v[190:193], v[230:233], v[106:109]
	v_mfma_f32_16x16x32_bf16 v[102:105], v[140:143], v[238:241], v[102:105]
	v_mfma_f32_16x16x32_bf16 v[98:101], v[190:193], v[238:241], v[98:101]
	v_mfma_f32_16x16x32_bf16 v[126:129], v[174:177], v[218:221], v[126:129]
	v_mfma_f32_16x16x32_bf16 v[122:125], v[194:197], v[218:221], v[122:125]
	v_mfma_f32_16x16x32_bf16 v[118:121], v[174:177], v[226:229], v[118:121]
	v_mfma_f32_16x16x32_bf16 v[114:117], v[194:197], v[226:229], v[114:117]
	v_mfma_f32_16x16x32_bf16 v[110:113], v[174:177], v[234:237], v[110:113]
	v_mfma_f32_16x16x32_bf16 v[106:109], v[194:197], v[234:237], v[106:109]
	v_mfma_f32_16x16x32_bf16 v[102:105], v[174:177], v[242:245], v[102:105]
	v_mfma_f32_16x16x32_bf16 v[98:101], v[194:197], v[242:245], v[98:101]
	s_setprio 0
	s_setprio 1
	v_mfma_f32_16x16x32_bf16 v[62:65], v[198:201], v[214:217], v[62:65]
	v_mfma_f32_16x16x32_bf16 v[58:61], v[206:209], v[214:217], v[58:61]
	v_mfma_f32_16x16x32_bf16 v[54:57], v[198:201], v[222:225], v[54:57]
	v_mfma_f32_16x16x32_bf16 v[50:53], v[206:209], v[222:225], v[50:53]
	v_mfma_f32_16x16x32_bf16 v[46:49], v[198:201], v[230:233], v[46:49]
	v_mfma_f32_16x16x32_bf16 v[42:45], v[206:209], v[230:233], v[42:45]
	v_mfma_f32_16x16x32_bf16 v[38:41], v[198:201], v[238:241], v[38:41]
	v_mfma_f32_16x16x32_bf16 v[34:37], v[206:209], v[238:241], v[34:37]
	v_mfma_f32_16x16x32_bf16 v[62:65], v[202:205], v[218:221], v[62:65]
	v_mfma_f32_16x16x32_bf16 v[58:61], v[210:213], v[218:221], v[58:61]
	v_mfma_f32_16x16x32_bf16 v[54:57], v[202:205], v[226:229], v[54:57]
	v_mfma_f32_16x16x32_bf16 v[50:53], v[210:213], v[226:229], v[50:53]
	v_mfma_f32_16x16x32_bf16 v[46:49], v[202:205], v[234:237], v[46:49]
	v_mfma_f32_16x16x32_bf16 v[42:45], v[210:213], v[234:237], v[42:45]
	v_mfma_f32_16x16x32_bf16 v[38:41], v[202:205], v[242:245], v[38:41]
	v_mfma_f32_16x16x32_bf16 v[34:37], v[210:213], v[242:245], v[34:37]
	s_setprio 0
	s_barrier
	s_add_i32 s3, s3, s26
	v_lshl_add_u64 v[144:145], s[0:1], 0, v[4:5]
	s_mov_b32 m0, s3
	ds_read_b128 v[214:217], v172 offset:16384
	ds_read_b128 v[218:221], v172 offset:17408
	ds_read_b128 v[222:225], v172 offset:18432
	ds_read_b128 v[226:229], v172 offset:19456
	ds_read_b128 v[230:233], v172 offset:20480
	ds_read_b128 v[234:237], v172 offset:21504
	ds_read_b128 v[238:241], v172 offset:22528
	ds_read_b128 v[242:245], v172 offset:23552
	global_load_lds_dwordx4 v[144:145], off
	s_add_i32 m0, s3, 0x2000
	s_add_u32 s4, s0, 0x40000
	v_lshl_add_u64 v[246:247], s[0:1], 0, v[134:135]
	s_addc_u32 s5, s1, 0
	s_add_i32 s3, s6, s26
	global_load_lds_dwordx4 v[246:247], off
	v_lshl_add_u64 v[248:249], s[4:5], 0, v[4:5]
	s_mov_b32 m0, s3
	v_lshl_add_u64 v[250:251], s[14:15], 0, v[132:133]
	global_load_lds_dwordx4 v[248:249], off
	v_lshl_add_u64 v[248:249], s[4:5], 0, v[134:135]
	s_add_i32 m0, s3, 0x2000
	s_nop 0
	global_load_lds_dwordx4 v[248:249], off
	v_lshl_add_u64 v[248:249], s[14:15], 0, v[130:131]
	s_mov_b32 m0, s27
	s_nop 0
	global_load_lds_dwordx4 v[248:249], off
	s_mov_b32 m0, s30
	s_nop 0
	global_load_lds_dwordx4 v[250:251], off
	s_waitcnt vmcnt(40)
	s_waitcnt lgkmcnt(0)
	s_barrier
	s_setprio 1
	s_waitcnt lgkmcnt(0)
	v_mfma_f32_16x16x32_bf16 v[94:97], v[140:143], v[214:217], v[94:97]
	v_mfma_f32_16x16x32_bf16 v[90:93], v[190:193], v[214:217], v[90:93]
	v_mfma_f32_16x16x32_bf16 v[86:89], v[140:143], v[222:225], v[86:89]
	v_mfma_f32_16x16x32_bf16 v[82:85], v[190:193], v[222:225], v[82:85]
	v_mfma_f32_16x16x32_bf16 v[78:81], v[140:143], v[230:233], v[78:81]
	v_mfma_f32_16x16x32_bf16 v[74:77], v[190:193], v[230:233], v[74:77]
	v_mfma_f32_16x16x32_bf16 v[70:73], v[140:143], v[238:241], v[70:73]
	v_mfma_f32_16x16x32_bf16 v[66:69], v[190:193], v[238:241], v[66:69]
	v_mfma_f32_16x16x32_bf16 v[94:97], v[174:177], v[218:221], v[94:97]
	v_mfma_f32_16x16x32_bf16 v[90:93], v[194:197], v[218:221], v[90:93]
	v_mfma_f32_16x16x32_bf16 v[86:89], v[174:177], v[226:229], v[86:89]
	v_mfma_f32_16x16x32_bf16 v[82:85], v[194:197], v[226:229], v[82:85]
	v_mfma_f32_16x16x32_bf16 v[78:81], v[174:177], v[234:237], v[78:81]
	v_mfma_f32_16x16x32_bf16 v[74:77], v[194:197], v[234:237], v[74:77]
	v_mfma_f32_16x16x32_bf16 v[70:73], v[174:177], v[242:245], v[70:73]
	v_mfma_f32_16x16x32_bf16 v[66:69], v[194:197], v[242:245], v[66:69]
	s_setprio 0
	s_setprio 1
	v_mfma_f32_16x16x32_bf16 v[30:33], v[198:201], v[214:217], v[30:33]
	v_mfma_f32_16x16x32_bf16 v[26:29], v[206:209], v[214:217], v[26:29]
	v_mfma_f32_16x16x32_bf16 v[22:25], v[198:201], v[222:225], v[22:25]
	v_mfma_f32_16x16x32_bf16 v[18:21], v[206:209], v[222:225], v[18:21]
	v_mfma_f32_16x16x32_bf16 v[14:17], v[198:201], v[230:233], v[14:17]
	v_mfma_f32_16x16x32_bf16 v[10:13], v[206:209], v[230:233], v[10:13]
	v_mfma_f32_16x16x32_bf16 v[6:9], v[198:201], v[238:241], v[6:9]
	v_mfma_f32_16x16x32_bf16 v[0:3], v[206:209], v[238:241], v[0:3]
	v_mfma_f32_16x16x32_bf16 v[30:33], v[202:205], v[218:221], v[30:33]
	v_mfma_f32_16x16x32_bf16 v[26:29], v[210:213], v[218:221], v[26:29]
	v_mfma_f32_16x16x32_bf16 v[22:25], v[202:205], v[226:229], v[22:25]
	v_mfma_f32_16x16x32_bf16 v[18:21], v[210:213], v[226:229], v[18:21]
	v_mfma_f32_16x16x32_bf16 v[14:17], v[202:205], v[234:237], v[14:17]
	v_mfma_f32_16x16x32_bf16 v[10:13], v[210:213], v[234:237], v[10:13]
	v_mfma_f32_16x16x32_bf16 v[6:9], v[202:205], v[242:245], v[6:9]
	v_mfma_f32_16x16x32_bf16 v[0:3], v[210:213], v[242:245], v[0:3]
	s_setprio 0
	s_barrier
	s_branch .Lpeelmid_205

.LBB0_227:
	s_ashr_i32 s47, s46, 31
	s_lshl_b64 s[2:3], s[46:47], 19
	v_readlane_b32 s4, v253, 25
	v_readlane_b32 s5, v253, 26
	s_add_u32 s82, s4, s2
	s_addc_u32 s83, s5, s3
	s_and_b64 s[2:3], s[40:41], exec
	s_cselect_b32 s2, s83, s15
	s_cselect_b32 s8, s82, s14
	s_add_u32 s22, s0, 0x40080
	s_addc_u32 s23, s1, 0
	s_add_u32 s9, s14, 0x100
	v_mov_b32_e32 v0, 0
	s_addc_u32 s10, s15, 0
	s_mov_b32 s24, -2
	v_mov_b32_e32 v1, v0
	v_mov_b32_e32 v2, v0
	v_mov_b32_e32 v3, v0
	v_mov_b32_e32 v6, v0
	v_mov_b32_e32 v7, v0
	v_mov_b32_e32 v8, v0
	v_mov_b32_e32 v9, v0
	v_mov_b32_e32 v10, v0
	v_mov_b32_e32 v11, v0
	v_mov_b32_e32 v12, v0
	v_mov_b32_e32 v13, v0
	v_mov_b32_e32 v14, v0
	v_mov_b32_e32 v15, v0
	v_mov_b32_e32 v16, v0
	v_mov_b32_e32 v17, v0
	v_mov_b32_e32 v18, v0
	v_mov_b32_e32 v19, v0
	v_mov_b32_e32 v20, v0
	v_mov_b32_e32 v21, v0
	v_mov_b32_e32 v22, v0
	v_mov_b32_e32 v23, v0
	v_mov_b32_e32 v24, v0
	v_mov_b32_e32 v25, v0
	v_mov_b32_e32 v26, v0
	v_mov_b32_e32 v27, v0
	v_mov_b32_e32 v28, v0
	v_mov_b32_e32 v29, v0
	v_mov_b32_e32 v30, v0
	v_mov_b32_e32 v31, v0
	v_mov_b32_e32 v32, v0
	v_mov_b32_e32 v33, v0
	v_mov_b32_e32 v62, v0
	v_mov_b32_e32 v63, v0
	v_mov_b32_e32 v64, v0
	v_mov_b32_e32 v65, v0
	v_mov_b32_e32 v70, v0
	v_mov_b32_e32 v71, v0
	v_mov_b32_e32 v72, v0
	v_mov_b32_e32 v73, v0
	v_mov_b32_e32 v74, v0
	v_mov_b32_e32 v75, v0
	v_mov_b32_e32 v76, v0
	v_mov_b32_e32 v77, v0
	v_mov_b32_e32 v78, v0
	v_mov_b32_e32 v79, v0
	v_mov_b32_e32 v80, v0
	v_mov_b32_e32 v81, v0
	v_mov_b32_e32 v82, v0
	v_mov_b32_e32 v83, v0
	v_mov_b32_e32 v84, v0
	v_mov_b32_e32 v85, v0
	v_mov_b32_e32 v86, v0
	v_mov_b32_e32 v87, v0
	v_mov_b32_e32 v88, v0
	v_mov_b32_e32 v89, v0
	v_mov_b32_e32 v90, v0
	v_mov_b32_e32 v91, v0
	v_mov_b32_e32 v92, v0
	v_mov_b32_e32 v93, v0
	v_mov_b32_e32 v94, v0
	v_mov_b32_e32 v95, v0
	v_mov_b32_e32 v96, v0
	v_mov_b32_e32 v97, v0
	v_mov_b32_e32 v34, v0
	v_mov_b32_e32 v35, v0
	v_mov_b32_e32 v36, v0
	v_mov_b32_e32 v37, v0
	v_mov_b32_e32 v38, v0
	v_mov_b32_e32 v39, v0
	v_mov_b32_e32 v40, v0
	v_mov_b32_e32 v41, v0
	v_mov_b32_e32 v42, v0
	v_mov_b32_e32 v43, v0
	v_mov_b32_e32 v44, v0
	v_mov_b32_e32 v45, v0
	v_mov_b32_e32 v46, v0
	v_mov_b32_e32 v47, v0
	v_mov_b32_e32 v48, v0
	v_mov_b32_e32 v49, v0
	v_mov_b32_e32 v50, v0
	v_mov_b32_e32 v51, v0
	v_mov_b32_e32 v52, v0
	v_mov_b32_e32 v53, v0
	v_mov_b32_e32 v54, v0
	v_mov_b32_e32 v55, v0
	v_mov_b32_e32 v56, v0
	v_mov_b32_e32 v57, v0
	v_mov_b32_e32 v58, v0
	v_mov_b32_e32 v59, v0
	v_mov_b32_e32 v60, v0
	v_mov_b32_e32 v61, v0
	v_mov_b32_e32 v66, v0
	v_mov_b32_e32 v67, v0
	v_mov_b32_e32 v68, v0
	v_mov_b32_e32 v69, v0
	v_mov_b32_e32 v98, v0
	v_mov_b32_e32 v99, v0
	v_mov_b32_e32 v100, v0
	v_mov_b32_e32 v101, v0
	v_mov_b32_e32 v102, v0
	v_mov_b32_e32 v103, v0
	v_mov_b32_e32 v104, v0
	v_mov_b32_e32 v105, v0
	v_mov_b32_e32 v106, v0
	v_mov_b32_e32 v107, v0
	v_mov_b32_e32 v108, v0
	v_mov_b32_e32 v109, v0
	v_mov_b32_e32 v110, v0
	v_mov_b32_e32 v111, v0
	v_mov_b32_e32 v112, v0
	v_mov_b32_e32 v113, v0
	v_mov_b32_e32 v114, v0
	v_mov_b32_e32 v115, v0
	v_mov_b32_e32 v116, v0
	v_mov_b32_e32 v117, v0
	v_mov_b32_e32 v118, v0
	v_mov_b32_e32 v119, v0
	v_mov_b32_e32 v120, v0
	v_mov_b32_e32 v121, v0
	v_mov_b32_e32 v122, v0
	v_mov_b32_e32 v123, v0
	v_mov_b32_e32 v124, v0
	v_mov_b32_e32 v125, v0
	v_mov_b32_e32 v126, v0
	v_mov_b32_e32 v127, v0
	v_mov_b32_e32 v128, v0
	v_mov_b32_e32 v129, v0
	s_cmp_eq_u32 s37, 1
	s_cbranch_scc1 .LBB0_228
	s_add_u32 s0, s22, 0xfffc0080
	s_addc_u32 s1, s23, -1
	s_add_i32 s3, 0, 0x10000
	s_cmp_eq_u32 s24, 12
	s_cselect_b32 s15, s49, s1
	s_cselect_b32 s14, s48, s0
	v_add_u32_e32 v162, s3, v149
	s_cselect_b32 s1, s2, s10
	s_cselect_b32 s0, s8, s9
	s_add_i32 s6, 0, 0x14000
	ds_read_b128 v[140:143], v162
	ds_read_b128 v[144:147], v162 offset:1024
	ds_read_b128 v[172:175], v162 offset:2048
	ds_read_b128 v[190:193], v162 offset:3072
	v_add_u32_e32 v162, s6, v149
	ds_read_b128 v[194:197], v162
	ds_read_b128 v[198:201], v162 offset:1024
	ds_read_b128 v[202:205], v162 offset:2048
	ds_read_b128 v[206:209], v162 offset:3072
	v_lshl_add_u64 v[162:163], s[22:23], 0, v[136:137]
	s_add_i32 m0, s27, 0xc000
	ds_read_b128 v[210:213], v151
	ds_read_b128 v[214:217], v151 offset:1024
	ds_read_b128 v[218:221], v151 offset:2048
	ds_read_b128 v[222:225], v151 offset:3072
	ds_read_b128 v[226:229], v151 offset:4096
	ds_read_b128 v[230:233], v151 offset:5120
	ds_read_b128 v[234:237], v151 offset:6144
	ds_read_b128 v[238:241], v151 offset:7168
	global_load_lds_dwordx4 v[162:163], off
	v_lshl_add_u64 v[162:163], s[22:23], 0, v[138:139]
	s_add_i32 m0, s27, 0xe000
	s_nop 0
	global_load_lds_dwordx4 v[162:163], off
	s_waitcnt vmcnt(56)
	s_waitcnt lgkmcnt(0)
	s_barrier
	s_setprio 1
	s_waitcnt lgkmcnt(0)
	v_mfma_f32_16x16x32_bf16 v[126:129], v[140:143], v[210:213], v[126:129]
	v_mfma_f32_16x16x32_bf16 v[122:125], v[172:175], v[210:213], v[122:125]
	v_mfma_f32_16x16x32_bf16 v[118:121], v[140:143], v[218:221], v[118:121]
	v_mfma_f32_16x16x32_bf16 v[114:117], v[172:175], v[218:221], v[114:117]
	v_mfma_f32_16x16x32_bf16 v[110:113], v[140:143], v[226:229], v[110:113]
	v_mfma_f32_16x16x32_bf16 v[106:109], v[172:175], v[226:229], v[106:109]
	v_mfma_f32_16x16x32_bf16 v[102:105], v[140:143], v[234:237], v[102:105]
	v_mfma_f32_16x16x32_bf16 v[98:101], v[172:175], v[234:237], v[98:101]
	v_mfma_f32_16x16x32_bf16 v[126:129], v[144:147], v[214:217], v[126:129]
	v_mfma_f32_16x16x32_bf16 v[122:125], v[190:193], v[214:217], v[122:125]
	v_mfma_f32_16x16x32_bf16 v[118:121], v[144:147], v[222:225], v[118:121]
	v_mfma_f32_16x16x32_bf16 v[114:117], v[190:193], v[222:225], v[114:117]
	v_mfma_f32_16x16x32_bf16 v[110:113], v[144:147], v[230:233], v[110:113]
	v_mfma_f32_16x16x32_bf16 v[106:109], v[190:193], v[230:233], v[106:109]
	v_mfma_f32_16x16x32_bf16 v[102:105], v[144:147], v[238:241], v[102:105]
	v_mfma_f32_16x16x32_bf16 v[98:101], v[190:193], v[238:241], v[98:101]
	s_setprio 0
	s_setprio 1
	v_mfma_f32_16x16x32_bf16 v[66:69], v[194:197], v[210:213], v[66:69]
	v_mfma_f32_16x16x32_bf16 v[58:61], v[202:205], v[210:213], v[58:61]
	v_mfma_f32_16x16x32_bf16 v[54:57], v[194:197], v[218:221], v[54:57]
	v_mfma_f32_16x16x32_bf16 v[50:53], v[202:205], v[218:221], v[50:53]
	v_mfma_f32_16x16x32_bf16 v[46:49], v[194:197], v[226:229], v[46:49]
	v_mfma_f32_16x16x32_bf16 v[42:45], v[202:205], v[226:229], v[42:45]
	v_mfma_f32_16x16x32_bf16 v[38:41], v[194:197], v[234:237], v[38:41]
	v_mfma_f32_16x16x32_bf16 v[34:37], v[202:205], v[234:237], v[34:37]
	v_mfma_f32_16x16x32_bf16 v[66:69], v[198:201], v[214:217], v[66:69]
	v_mfma_f32_16x16x32_bf16 v[58:61], v[206:209], v[214:217], v[58:61]
	v_mfma_f32_16x16x32_bf16 v[54:57], v[198:201], v[222:225], v[54:57]
	v_mfma_f32_16x16x32_bf16 v[50:53], v[206:209], v[222:225], v[50:53]
	v_mfma_f32_16x16x32_bf16 v[46:49], v[198:201], v[230:233], v[46:49]
	v_mfma_f32_16x16x32_bf16 v[42:45], v[206:209], v[230:233], v[42:45]
	v_mfma_f32_16x16x32_bf16 v[38:41], v[198:201], v[238:241], v[38:41]
	v_mfma_f32_16x16x32_bf16 v[34:37], v[206:209], v[238:241], v[34:37]
	s_setprio 0
	s_barrier
	s_add_i32 s3, s3, s26
	v_lshl_add_u64 v[162:163], s[0:1], 0, v[4:5]
	s_mov_b32 m0, s3
	ds_read_b128 v[210:213], v151 offset:16384
	ds_read_b128 v[214:217], v151 offset:17408
	ds_read_b128 v[218:221], v151 offset:18432
	ds_read_b128 v[222:225], v151 offset:19456
	ds_read_b128 v[226:229], v151 offset:20480
	ds_read_b128 v[230:233], v151 offset:21504
	ds_read_b128 v[234:237], v151 offset:22528
	ds_read_b128 v[238:241], v151 offset:23552
	global_load_lds_dwordx4 v[162:163], off
	s_add_i32 m0, s3, 0x2000
	s_add_u32 s4, s0, 0x40000
	v_lshl_add_u64 v[166:167], s[0:1], 0, v[134:135]
	s_addc_u32 s5, s1, 0
	s_add_i32 s3, s6, s26
	global_load_lds_dwordx4 v[166:167], off
	v_lshl_add_u64 v[176:177], s[4:5], 0, v[4:5]
	s_mov_b32 m0, s3
	v_lshl_add_u64 v[180:181], s[14:15], 0, v[132:133]
	global_load_lds_dwordx4 v[176:177], off
	v_lshl_add_u64 v[176:177], s[4:5], 0, v[134:135]
	s_add_i32 m0, s3, 0x2000
	s_nop 0
	global_load_lds_dwordx4 v[176:177], off
	v_lshl_add_u64 v[176:177], s[14:15], 0, v[130:131]
	s_mov_b32 m0, s27
	s_nop 0
	global_load_lds_dwordx4 v[176:177], off
	s_mov_b32 m0, s30
	s_nop 0
	global_load_lds_dwordx4 v[180:181], off
	s_waitcnt vmcnt(56)
	s_waitcnt lgkmcnt(0)
	s_barrier
	s_setprio 1
	s_waitcnt lgkmcnt(0)
	v_mfma_f32_16x16x32_bf16 v[94:97], v[140:143], v[210:213], v[94:97]
	v_mfma_f32_16x16x32_bf16 v[90:93], v[172:175], v[210:213], v[90:93]
	v_mfma_f32_16x16x32_bf16 v[86:89], v[140:143], v[218:221], v[86:89]
	v_mfma_f32_16x16x32_bf16 v[82:85], v[172:175], v[218:221], v[82:85]
	v_mfma_f32_16x16x32_bf16 v[78:81], v[140:143], v[226:229], v[78:81]
	v_mfma_f32_16x16x32_bf16 v[74:77], v[172:175], v[226:229], v[74:77]
	v_mfma_f32_16x16x32_bf16 v[70:73], v[140:143], v[234:237], v[70:73]
	v_mfma_f32_16x16x32_bf16 v[62:65], v[172:175], v[234:237], v[62:65]
	v_mfma_f32_16x16x32_bf16 v[94:97], v[144:147], v[214:217], v[94:97]
	v_mfma_f32_16x16x32_bf16 v[90:93], v[190:193], v[214:217], v[90:93]
	v_mfma_f32_16x16x32_bf16 v[86:89], v[144:147], v[222:225], v[86:89]
	v_mfma_f32_16x16x32_bf16 v[82:85], v[190:193], v[222:225], v[82:85]
	v_mfma_f32_16x16x32_bf16 v[78:81], v[144:147], v[230:233], v[78:81]
	v_mfma_f32_16x16x32_bf16 v[74:77], v[190:193], v[230:233], v[74:77]
	v_mfma_f32_16x16x32_bf16 v[70:73], v[144:147], v[238:241], v[70:73]
	v_mfma_f32_16x16x32_bf16 v[62:65], v[190:193], v[238:241], v[62:65]
	s_setprio 0
	s_setprio 1
	v_mfma_f32_16x16x32_bf16 v[30:33], v[194:197], v[210:213], v[30:33]
	v_mfma_f32_16x16x32_bf16 v[26:29], v[202:205], v[210:213], v[26:29]
	v_mfma_f32_16x16x32_bf16 v[22:25], v[194:197], v[218:221], v[22:25]
	v_mfma_f32_16x16x32_bf16 v[18:21], v[202:205], v[218:221], v[18:21]
	v_mfma_f32_16x16x32_bf16 v[14:17], v[194:197], v[226:229], v[14:17]
	v_mfma_f32_16x16x32_bf16 v[10:13], v[202:205], v[226:229], v[10:13]
	v_mfma_f32_16x16x32_bf16 v[6:9], v[194:197], v[234:237], v[6:9]
	v_mfma_f32_16x16x32_bf16 v[0:3], v[202:205], v[234:237], v[0:3]
	v_mfma_f32_16x16x32_bf16 v[30:33], v[198:201], v[214:217], v[30:33]
	v_mfma_f32_16x16x32_bf16 v[26:29], v[206:209], v[214:217], v[26:29]
	v_mfma_f32_16x16x32_bf16 v[22:25], v[198:201], v[222:225], v[22:25]
	v_mfma_f32_16x16x32_bf16 v[18:21], v[206:209], v[222:225], v[18:21]
	v_mfma_f32_16x16x32_bf16 v[14:17], v[198:201], v[230:233], v[14:17]
	v_mfma_f32_16x16x32_bf16 v[10:13], v[206:209], v[230:233], v[10:13]
	v_mfma_f32_16x16x32_bf16 v[6:9], v[198:201], v[238:241], v[6:9]
	v_mfma_f32_16x16x32_bf16 v[0:3], v[206:209], v[238:241], v[0:3]
	s_setprio 0
	s_barrier
	s_branch .Lpeelmid_228
